# v12 + lru_job serial scan loop with batched LDS reads + la_job/gla_job intra-chunk stage straightened (exec-skip branches dropped) and its LDS reads hoisted
# baseline (speedup 1.0000x reference)
.LBB0_719:
	ds_read_b128 v[70:73], v233
	s_add_u32 s22, s77, s71
	s_addc_u32 s23, 0, s72
	v_cmp_gt_i32_e32 vcc, s78, v161
	s_waitcnt lgkmcnt(1)
	s_waitcnt lgkmcnt(0)
	v_mfma_f32_16x16x32_bf16 v[150:153], v[134:137], v[70:73], v[150:153]
	ds_read_b128 v[70:73], v233 offset:2304
	ds_read_b128 v[74:77], v233 offset:2368
	ds_read_b128 v[78:81], v233 offset:4608
	ds_read_b128 v[82:85], v233 offset:4672
	ds_read_b128 v[86:89], v233 offset:6912
	ds_read_b128 v[234:237], v233 offset:64
	s_waitcnt lgkmcnt(0)
	v_mfma_f32_16x16x32_bf16 v[150:153], v[130:133], v[234:237], v[150:153]
	ds_read_b128 v[90:93], v233 offset:6976
	s_and_saveexec_b64 s[24:25], vcc
	s_nop 0
	v_mov_b32_e32 v235, s23
	v_or_b32_e32 v234, s22, v161
	v_lshlrev_b64 v[234:235], 13, v[234:235]
	s_nop 2
	v_cvt_pk_bf16_f32 v36, v150, v151
	v_cvt_pk_bf16_f32 v37, v152, v153
	v_lshl_add_u64 v[234:235], v[176:177], 0, v[234:235]
	global_store_dwordx2 v[234:235], v[36:37], off
	s_or_b64 exec, exec, s[24:25]
	v_and_b32_e32 v35, 64, v229
	v_xor_b32_e32 v1, 16, v229
	v_add_u32_e32 v36, 64, v35
	v_cmp_lt_i32_e32 vcc, v1, v36
	s_nop 0
	v_mul_f32_e32 v37, v153, v153
	v_fmac_f32_e32 v37, v152, v152
	v_cndmask_b32_e32 v1, v229, v1, vcc
	v_lshlrev_b32_e32 v35, 2, v1
	v_mul_f32_e32 v1, v151, v151
	v_fmac_f32_e32 v1, v150, v150
	v_add_f32_e32 v1, v1, v37
	ds_bpermute_b32 v37, v35, v1
	v_xor_b32_e32 v150, 32, v229
	v_cmp_lt_i32_e32 vcc, v150, v36
	s_waitcnt lgkmcnt(0)
	v_add_f32_e32 v37, v1, v37
	v_cndmask_b32_e32 v36, v229, v150, vcc
	v_lshlrev_b32_e32 v36, 2, v36
	ds_bpermute_b32 v150, v36, v37
	s_and_saveexec_b64 s[24:25], s[38:39]
	s_nop 0
	s_waitcnt lgkmcnt(0)
	v_add_f32_e32 v1, v37, v150
	ds_write_b32 v214, v1
	s_or_b64 exec, exec, s[24:25]
	s_min_i32 s26, s78, 64
	v_cmp_gt_i32_e32 vcc, s26, v162
	v_mfma_f32_16x16x32_bf16 v[146:149], v[134:137], v[70:73], v[146:149]
	s_nop 0
	v_mfma_f32_16x16x32_bf16 v[146:149], v[130:133], v[74:77], v[146:149]
	s_and_saveexec_b64 s[24:25], vcc
	s_nop 0
	v_mov_b32_e32 v153, s23
	v_or_b32_e32 v152, s22, v162
	v_lshlrev_b64 v[152:153], 13, v[152:153]
	s_nop 2
	v_cvt_pk_bf16_f32 v150, v146, v147
	v_cvt_pk_bf16_f32 v151, v148, v149
	v_lshl_add_u64 v[152:153], v[176:177], 0, v[152:153]
	global_store_dwordx2 v[152:153], v[150:151], off
	s_or_b64 exec, exec, s[24:25]
	s_nop 4
	v_mul_f32_e32 v1, v147, v147
	v_mul_f32_e32 v37, v149, v149
	v_fmac_f32_e32 v1, v146, v146
	v_fmac_f32_e32 v37, v148, v148
	v_add_f32_e32 v1, v1, v37
	ds_bpermute_b32 v37, v35, v1
	s_waitcnt lgkmcnt(0)
	v_add_f32_e32 v37, v1, v37
	ds_bpermute_b32 v146, v36, v37
	s_and_saveexec_b64 s[24:25], s[38:39]
	s_nop 0
	s_waitcnt lgkmcnt(0)
	v_add_f32_e32 v1, v37, v146
	ds_write_b32 v215, v1
	s_or_b64 exec, exec, s[24:25]
	v_cmp_gt_i32_e32 vcc, s26, v172
	v_mfma_f32_16x16x32_bf16 v[142:145], v[134:137], v[78:81], v[142:145]
	s_nop 0
	s_nop 0
	v_mfma_f32_16x16x32_bf16 v[142:145], v[130:133], v[82:85], v[142:145]
	s_and_saveexec_b64 s[24:25], vcc
	s_nop 0
	v_lshl_add_u64 v[148:149], s[22:23], 0, v[172:173]
	v_lshlrev_b64 v[148:149], 13, v[148:149]
	s_nop 3
	v_cvt_pk_bf16_f32 v146, v142, v143
	v_cvt_pk_bf16_f32 v147, v144, v145
	v_lshl_add_u64 v[148:149], v[176:177], 0, v[148:149]
	global_store_dwordx2 v[148:149], v[146:147], off
	s_or_b64 exec, exec, s[24:25]
	s_nop 4
	v_mul_f32_e32 v1, v143, v143
	v_mul_f32_e32 v37, v145, v145
	v_fmac_f32_e32 v1, v142, v142
	v_fmac_f32_e32 v37, v144, v144
	v_add_f32_e32 v1, v1, v37
	ds_bpermute_b32 v37, v35, v1
	s_waitcnt lgkmcnt(0)
	v_add_f32_e32 v37, v1, v37
	ds_bpermute_b32 v142, v36, v37
	s_and_saveexec_b64 s[24:25], s[38:39]
	s_nop 0
	s_waitcnt lgkmcnt(0)
	v_add_f32_e32 v1, v37, v142
	ds_write_b32 v216, v1
	s_or_b64 exec, exec, s[24:25]
	v_cmp_gt_i32_e32 vcc, s26, v174
	v_mfma_f32_16x16x32_bf16 v[138:141], v[134:137], v[86:89], v[138:141]
	s_nop 0
	s_nop 0
	v_mfma_f32_16x16x32_bf16 v[138:141], v[130:133], v[90:93], v[138:141]
	s_and_saveexec_b64 s[24:25], vcc
	s_nop 0
	v_lshl_add_u64 v[144:145], s[22:23], 0, v[174:175]
	v_lshlrev_b64 v[144:145], 13, v[144:145]
	s_nop 3
	v_cvt_pk_bf16_f32 v142, v138, v139
	v_cvt_pk_bf16_f32 v143, v140, v141
	v_lshl_add_u64 v[144:145], v[176:177], 0, v[144:145]
	global_store_dwordx2 v[144:145], v[142:143], off
	s_or_b64 exec, exec, s[24:25]
	s_nop 4
	v_mul_f32_e32 v1, v139, v139
	v_mul_f32_e32 v37, v141, v141
	v_fmac_f32_e32 v1, v138, v138
	v_fmac_f32_e32 v37, v140, v140
	v_add_f32_e32 v1, v1, v37
	ds_bpermute_b32 v35, v35, v1
	s_waitcnt lgkmcnt(0)
	v_add_f32_e32 v35, v1, v35
	ds_bpermute_b32 v36, v36, v35
	s_and_saveexec_b64 s[24:25], s[38:39]
	s_cbranch_execz .LBB0_735
	s_waitcnt lgkmcnt(0)
	v_add_f32_e32 v1, v35, v36
	ds_write_b32 v217, v1

.LBB0_839:
	s_nop 7
	v_cndmask_b32_e64 v1, v66, 0, s[54:55]
	v_cndmask_b32_e64 v35, v67, 0, s[56:57]
	v_cndmask_b32_e64 v37, v68, 0, s[58:59]
	v_cndmask_b32_e64 v67, v69, 0, s[60:61]
	v_cvt_pk_bf16_f32 v66, v1, v35
	v_cvt_pk_bf16_f32 v67, v37, v67
	ds_write_b64 v161, v[66:67]
	ds_read_b128 v[184:187], v132
	ds_read_b128 v[188:191], v135
	v_add_u32_e32 v1, 0x1000, v162
	ds_read_b64 v[192:193], v1 offset:256
	ds_read_b64 v[194:195], v1 offset:288
	ds_read_b64 v[196:197], v162
	ds_read_b64 v[198:199], v162 offset:32
	v_add_u32_e32 v35, 0x2000, v162
	ds_read_b64 v[200:201], v35 offset:512
	ds_read_b64 v[202:203], v35 offset:544
	v_add_u32_e32 v37, 0x3000, v162
	ds_read_b64 v[204:205], v37 offset:768
	ds_read_b64 v[206:207], v37 offset:800
	s_waitcnt lgkmcnt(11)
	s_waitcnt lgkmcnt(9)
	v_pk_mul_f32 v[68:69], v[4:5], v[186:187]
	ds_read_b128 v[208:211], v136
	v_pk_mul_f32 v[66:67], v[2:3], v[184:185]
	s_waitcnt lgkmcnt(9)
	v_pk_mul_f32 v[72:73], v[12:13], v[190:191]
	ds_read_b128 v[184:187], v137
	v_cvt_pk_bf16_f32 v66, v66, v67
	v_cvt_pk_bf16_f32 v67, v68, v69
	v_pk_mul_f32 v[68:69], v[10:11], v[188:189]
	v_cvt_pk_bf16_f32 v68, v68, v69
	v_cvt_pk_bf16_f32 v69, v72, v73
	s_nop 0
	s_waitcnt lgkmcnt(6)
	v_mfma_f32_16x16x32_bf16 v[70:73], v[66:69], v[196:199], 0
	s_sub_i32 s5, s8, 64
	s_add_u32 s18, s5, s72
	s_addc_u32 s19, 0, s74
	v_mfma_f32_16x16x32_bf16 v[74:77], v[66:69], v[192:195], 0
	ds_read_b64 v[188:189], v162 offset:64
	ds_read_b64 v[190:191], v162 offset:96
	ds_read_b64 v[192:193], v1 offset:320
	ds_read_b64 v[194:195], v1 offset:352
	v_mov_b32_e32 v36, 0
	v_cmp_gt_i32_e64 s[68:69], s9, v95
	v_or_b32_e32 v116, s18, v95
	s_waitcnt lgkmcnt(8)
	v_mfma_f32_16x16x32_bf16 v[78:81], v[66:69], v[200:203], 0
	ds_read_b64 v[196:197], v35 offset:576
	ds_read_b64 v[198:199], v35 offset:608
	s_waitcnt lgkmcnt(8)
	v_mfma_f32_16x16x32_bf16 v[66:69], v[66:69], v[204:207], 0
	ds_read_b64 v[200:201], v37 offset:832
	ds_read_b64 v[202:203], v37 offset:864
	s_waitcnt lgkmcnt(9)
	v_pk_mul_f32 v[106:107], v[8:9], v[210:211]
	ds_read_b128 v[204:207], v138
	v_pk_mul_f32 v[104:105], v[6:7], v[208:209]
	s_waitcnt lgkmcnt(9)
	v_pk_mul_f32 v[110:111], v[16:17], v[186:187]
	ds_read_b128 v[208:211], v139
	v_cvt_pk_bf16_f32 v104, v104, v105
	v_cvt_pk_bf16_f32 v105, v106, v107
	v_pk_mul_f32 v[106:107], v[14:15], v[184:185]
	s_nop 0
	v_cvt_pk_bf16_f32 v106, v106, v107
	v_cvt_pk_bf16_f32 v107, v110, v111
	s_nop 0
	s_waitcnt lgkmcnt(8)
	v_mfma_f32_16x16x32_bf16 v[70:73], v[104:107], v[188:191], v[70:73]
	ds_read_b64 v[184:185], v162 offset:128
	ds_read_b64 v[186:187], v162 offset:160
	s_waitcnt lgkmcnt(8)
	v_mfma_f32_16x16x32_bf16 v[74:77], v[104:107], v[192:195], v[74:77]
	ds_read_b64 v[188:189], v1 offset:384
	ds_read_b64 v[190:191], v1 offset:416
	s_waitcnt lgkmcnt(8)
	v_mfma_f32_16x16x32_bf16 v[78:81], v[104:107], v[196:199], v[78:81]
	ds_read_b64 v[192:193], v35 offset:640
	ds_read_b64 v[194:195], v35 offset:672
	s_waitcnt lgkmcnt(8)
	v_mfma_f32_16x16x32_bf16 v[66:69], v[104:107], v[200:203], v[66:69]
	ds_read_b64 v[196:197], v37 offset:896
	ds_read_b64 v[198:199], v37 offset:928
	s_waitcnt lgkmcnt(9)
	v_pk_mul_f32 v[106:107], v[20:21], v[206:207]
	ds_read_b128 v[200:203], v140
	v_pk_mul_f32 v[104:105], v[18:19], v[204:205]
	s_waitcnt lgkmcnt(9)
	v_pk_mul_f32 v[110:111], v[24:25], v[210:211]
	ds_read_b128 v[204:207], v141
	v_cvt_pk_bf16_f32 v104, v104, v105
	v_cvt_pk_bf16_f32 v105, v106, v107
	v_pk_mul_f32 v[106:107], v[22:23], v[208:209]
	s_nop 0
	v_cvt_pk_bf16_f32 v106, v106, v107
	v_cvt_pk_bf16_f32 v107, v110, v111
	s_nop 0
	s_waitcnt lgkmcnt(8)
	v_mfma_f32_16x16x32_bf16 v[70:73], v[104:107], v[184:187], v[70:73]
	ds_read_b64 v[184:185], v162 offset:192
	ds_read_b64 v[186:187], v162 offset:224
	s_waitcnt lgkmcnt(8)
	v_mfma_f32_16x16x32_bf16 v[74:77], v[104:107], v[188:191], v[74:77]
	ds_read_b64 v[188:189], v1 offset:448
	ds_read_b64 v[190:191], v1 offset:480
	s_waitcnt lgkmcnt(8)
	v_mfma_f32_16x16x32_bf16 v[78:81], v[104:107], v[192:195], v[78:81]
	ds_read_b64 v[192:193], v35 offset:704
	ds_read_b64 v[194:195], v35 offset:736
	s_waitcnt lgkmcnt(8)
	v_mfma_f32_16x16x32_bf16 v[66:69], v[104:107], v[196:199], v[66:69]
	s_waitcnt lgkmcnt(7)
	v_pk_mul_f32 v[106:107], v[28:29], v[202:203]
	v_pk_mul_f32 v[104:105], v[26:27], v[200:201]
	s_waitcnt lgkmcnt(6)
	v_pk_mul_f32 v[110:111], v[32:33], v[206:207]
	v_cvt_pk_bf16_f32 v104, v104, v105
	v_cvt_pk_bf16_f32 v105, v106, v107
	v_pk_mul_f32 v[106:107], v[30:31], v[204:205]
	s_nop 0
	v_cvt_pk_bf16_f32 v106, v106, v107
	v_cvt_pk_bf16_f32 v107, v110, v111
	s_nop 0
	s_waitcnt lgkmcnt(4)
	v_mfma_f32_16x16x32_bf16 v[108:111], v[104:107], v[184:187], v[70:73]
	s_nop 2
	s_waitcnt lgkmcnt(2)
	v_mfma_f32_16x16x32_bf16 v[74:77], v[104:107], v[188:191], v[74:77]
	s_waitcnt lgkmcnt(0)
	v_mfma_f32_16x16x32_bf16 v[70:73], v[104:107], v[192:195], v[78:81]
	s_nop 2
	ds_read_b64 v[78:79], v37 offset:960
	ds_read_b64 v[80:81], v37 offset:992
	s_waitcnt lgkmcnt(0)
	v_mfma_f32_16x16x32_bf16 v[66:69], v[104:107], v[78:81], v[66:69]
	s_barrier
	ds_read_b128 v[184:187], v174
	ds_read_b128 v[188:191], v174 offset:64
	ds_read_b128 v[192:195], v174 offset:2304
	ds_read_b128 v[196:199], v174 offset:2368
	ds_read_b128 v[200:203], v174 offset:4608
	ds_read_b128 v[204:207], v174 offset:4672
	s_waitcnt lgkmcnt(6)
	s_waitcnt lgkmcnt(5)
	v_mfma_f32_16x16x32_bf16 v[78:81], v[62:65], v[184:187], v[108:111]
	ds_read_b128 v[184:187], v174 offset:6912
	v_mov_b32_e32 v37, 0
	s_waitcnt lgkmcnt(5)
	v_mfma_f32_16x16x32_bf16 v[78:81], v[58:61], v[188:191], v[78:81]
	ds_read_b128 v[188:191], v174 offset:6976
	s_and_saveexec_b64 s[20:21], s[68:69]
	s_nop 0
	v_mov_b32_e32 v117, s19
	v_lshlrev_b64 v[36:37], 12, v[116:117]
	v_lshl_add_u64 v[36:37], v[102:103], 0, v[36:37]
	global_load_dwordx2 v[36:37], v[36:37], off
	s_or_b64 exec, exec, s[20:21]
	v_and_b32_e32 v35, 64, v229
	v_xor_b32_e32 v1, 16, v229
	v_add_u32_e32 v90, 64, v35
	v_cmp_lt_i32_e32 vcc, v1, v90
	s_nop 0
	v_mul_f32_e32 v104, v81, v81
	v_fmac_f32_e32 v104, v80, v80
	v_cndmask_b32_e32 v1, v229, v1, vcc
	v_lshlrev_b32_e32 v35, 2, v1
	v_mul_f32_e32 v1, v79, v79
	v_fmac_f32_e32 v1, v78, v78
	v_add_f32_e32 v1, v1, v104
	ds_bpermute_b32 v104, v35, v1
	v_xor_b32_e32 v105, 32, v229
	v_cmp_lt_i32_e32 vcc, v105, v90
	s_waitcnt lgkmcnt(0)
	v_add_f32_e32 v104, v1, v104
	v_cndmask_b32_e32 v90, v229, v105, vcc
	v_lshlrev_b32_e32 v90, 2, v90
	ds_bpermute_b32 v105, v90, v104
	s_and_saveexec_b64 s[20:21], s[36:37]
	s_nop 0
	s_waitcnt lgkmcnt(0)
	v_add_f32_e32 v1, v104, v105
	v_add_u32_e32 v104, s95, v142
	ds_write_b32 v104, v1
	s_or_b64 exec, exec, s[20:21]
	s_min_i32 s5, s9, 64
	v_cmp_gt_i32_e64 s[66:67], s5, v94
	v_mov_b32_e32 v114, 0
	v_or_b32_e32 v112, s18, v94
	v_mfma_f32_16x16x32_bf16 v[74:77], v[62:65], v[192:195], v[74:77]
	v_mov_b32_e32 v115, 0
	v_mfma_f32_16x16x32_bf16 v[74:77], v[58:61], v[196:199], v[74:77]
	s_and_saveexec_b64 s[20:21], s[66:67]
	s_nop 0
	v_mov_b32_e32 v113, s19
	v_lshlrev_b64 v[104:105], 12, v[112:113]
	v_lshl_add_u64 v[104:105], v[102:103], 0, v[104:105]
	global_load_dwordx2 v[114:115], v[104:105], off
	s_or_b64 exec, exec, s[20:21]
	s_nop 4
	v_mul_f32_e32 v1, v75, v75
	v_mul_f32_e32 v104, v77, v77
	v_fmac_f32_e32 v1, v74, v74
	v_fmac_f32_e32 v104, v76, v76
	v_add_f32_e32 v1, v1, v104
	ds_bpermute_b32 v104, v35, v1
	s_waitcnt lgkmcnt(0)
	v_add_f32_e32 v104, v1, v104
	ds_bpermute_b32 v105, v90, v104
	s_and_saveexec_b64 s[20:21], s[36:37]
	s_nop 0
	s_waitcnt lgkmcnt(0)
	v_add_f32_e32 v1, v104, v105
	v_add_u32_e32 v104, s95, v143
	ds_write_b32 v104, v1
	s_or_b64 exec, exec, s[20:21]
	v_cmp_gt_i32_e64 s[64:65], s5, v96
	v_mov_b32_e32 v110, 0
	v_lshl_add_u64 v[108:109], s[18:19], 0, v[96:97]
	v_mov_b32_e32 v111, 0
	v_mfma_f32_16x16x32_bf16 v[70:73], v[62:65], v[200:203], v[70:73]
	v_mfma_f32_16x16x32_bf16 v[70:73], v[58:61], v[204:207], v[70:73]
	s_and_saveexec_b64 s[20:21], s[64:65]
	s_nop 0
	v_lshlrev_b64 v[104:105], 12, v[108:109]
	v_lshl_add_u64 v[104:105], v[102:103], 0, v[104:105]
	global_load_dwordx2 v[110:111], v[104:105], off
	s_or_b64 exec, exec, s[20:21]
	s_nop 4
	v_mul_f32_e32 v1, v71, v71
	v_mul_f32_e32 v104, v73, v73
	v_fmac_f32_e32 v1, v70, v70
	v_fmac_f32_e32 v104, v72, v72
	v_add_f32_e32 v1, v1, v104
	ds_bpermute_b32 v104, v35, v1
	s_waitcnt lgkmcnt(0)
	v_add_f32_e32 v104, v1, v104
	ds_bpermute_b32 v105, v90, v104
	s_and_saveexec_b64 s[20:21], s[36:37]
	s_nop 0
	s_waitcnt lgkmcnt(0)
	v_add_f32_e32 v1, v104, v105
	v_add_u32_e32 v104, s95, v145
	ds_write_b32 v104, v1
	s_or_b64 exec, exec, s[20:21]
	v_cmp_gt_i32_e64 s[62:63], s5, v98
	v_mfma_f32_16x16x32_bf16 v[66:69], v[62:65], v[184:187], v[66:69]
	v_mfma_f32_16x16x32_bf16 v[66:69], v[58:61], v[188:191], v[66:69]
	v_mov_b32_e32 v106, 0
	v_lshl_add_u64 v[104:105], s[18:19], 0, v[98:99]
	v_mov_b32_e32 v107, 0
	s_and_saveexec_b64 s[20:21], s[62:63]
	s_nop 0
	v_lshlrev_b64 v[106:107], 12, v[104:105]
	v_lshl_add_u64 v[106:107], v[102:103], 0, v[106:107]
	global_load_dwordx2 v[106:107], v[106:107], off
	s_or_b64 exec, exec, s[20:21]
	s_nop 1
	v_mul_f32_e32 v1, v67, v67
	v_mul_f32_e32 v113, v69, v69
	v_fmac_f32_e32 v1, v66, v66
	v_fmac_f32_e32 v113, v68, v68
	v_add_f32_e32 v1, v1, v113
	ds_bpermute_b32 v35, v35, v1
	s_waitcnt lgkmcnt(0)
	v_add_f32_e32 v35, v1, v35
	ds_bpermute_b32 v90, v90, v35
	s_and_saveexec_b64 s[20:21], s[36:37]
	s_nop 0
	s_waitcnt lgkmcnt(0)
	v_add_f32_e32 v1, v35, v90
	v_add_u32_e32 v35, s95, v146
	ds_write_b32 v35, v1
	s_or_b64 exec, exec, s[20:21]
	s_andn2_b64 vcc, exec, s[0:1]
	s_cbranch_vccnz .LBB0_873
	s_mov_b32 s5, s8
	s_ashr_i32 s1, s5, 31
	s_add_u32 s0, s5, s72
	s_addc_u32 s1, s1, s74
	s_sub_i32 s5, s4, s5
	s_min_i32 s5, s5, 64
	v_mov_b32_e32 v120, 0
	s_cmp_ge_i32 s75, s5
	v_mov_b32_e32 v91, 0
	s_cbranch_scc0 .LBB0_881
	s_cmp_ge_i32 s76, s5
	s_cbranch_scc0 .LBB0_882

.LBB0_1352:
	v_add_u32_e32 v1, s43, v90
	v_add_u32_e32 v38, 0x14400, v1
	s_waitcnt lgkmcnt(2)
	ds_read2st64_b32 v[184:185], v1 offset0:196 offset1:198
	ds_read2st64_b32 v[186:187], v1 offset0:200 offset1:202
	ds_read2st64_b32 v[188:189], v1 offset0:204 offset1:206
	ds_read2st64_b32 v[190:191], v1 offset0:208 offset1:210
	ds_read_b32 v200, v38
	ds_read_b32 v201, v38 offset:512
	ds_read_b32 v202, v38 offset:1024
	ds_read_b32 v203, v38 offset:1536
	ds_read_b32 v204, v38 offset:2048
	ds_read_b32 v205, v38 offset:2560
	ds_read_b32 v206, v38 offset:3072
	ds_read_b32 v207, v38 offset:3584
	s_addk_i32 s43, 0x2000
	s_cmpk_lg_u32 s43, 0x8000
	s_waitcnt lgkmcnt(7)
	v_fmac_f32_e32 v200, v59, v184
	ds_write_b32 v38, v200
	s_waitcnt lgkmcnt(7)
	v_fmac_f32_e32 v201, v200, v185
	ds_write_b32 v38, v201 offset:512
	s_waitcnt lgkmcnt(7)
	v_fmac_f32_e32 v202, v201, v186
	ds_write_b32 v38, v202 offset:1024
	s_waitcnt lgkmcnt(7)
	v_fmac_f32_e32 v203, v202, v187
	ds_write_b32 v38, v203 offset:1536
	s_waitcnt lgkmcnt(7)
	v_fmac_f32_e32 v204, v203, v188
	ds_write_b32 v38, v204 offset:2048
	s_waitcnt lgkmcnt(7)
	v_fmac_f32_e32 v205, v204, v189
	ds_write_b32 v38, v205 offset:2560
	s_waitcnt lgkmcnt(7)
	v_fmac_f32_e32 v206, v205, v190
	ds_write_b32 v38, v206 offset:3072
	s_waitcnt lgkmcnt(7)
	v_fmac_f32_e32 v207, v206, v191
	ds_write_b32 v38, v207 offset:3584
	s_waitcnt lgkmcnt(2)
	ds_read2st64_b32 v[192:193], v1 offset0:212 offset1:214
	ds_read2st64_b32 v[194:195], v1 offset0:216 offset1:218
	ds_read2st64_b32 v[196:197], v1 offset0:220 offset1:222
	ds_read2st64_b32 v[198:199], v1 offset0:224 offset1:226
	ds_read_b32 v208, v38 offset:4096
	ds_read_b32 v209, v38 offset:4608
	ds_read_b32 v210, v38 offset:5120
	ds_read_b32 v211, v38 offset:5632
	ds_read_b32 v212, v38 offset:6144
	ds_read_b32 v213, v38 offset:6656
	ds_read_b32 v214, v38 offset:7168
	ds_read_b32 v215, v38 offset:7680
	s_waitcnt lgkmcnt(7)
	v_fmac_f32_e32 v208, v207, v192
	ds_write_b32 v38, v208 offset:4096
	s_waitcnt lgkmcnt(7)
	v_fmac_f32_e32 v209, v208, v193
	ds_write_b32 v38, v209 offset:4608
	s_waitcnt lgkmcnt(7)
	v_fmac_f32_e32 v210, v209, v194
	ds_write_b32 v38, v210 offset:5120
	s_waitcnt lgkmcnt(7)
	v_fmac_f32_e32 v211, v210, v195
	ds_write_b32 v38, v211 offset:5632
	s_waitcnt lgkmcnt(7)
	v_fmac_f32_e32 v212, v211, v196
	ds_write_b32 v38, v212 offset:6144
	s_waitcnt lgkmcnt(7)
	v_fmac_f32_e32 v213, v212, v197
	ds_write_b32 v38, v213 offset:6656
	s_waitcnt lgkmcnt(7)
	v_fmac_f32_e32 v214, v213, v198
	ds_write_b32 v38, v214 offset:7168
	s_waitcnt lgkmcnt(7)
	v_fmac_f32_e32 v215, v214, v199
	ds_write_b32 v38, v215 offset:7680
	v_mov_b32_e32 v59, v215
	s_cbranch_scc1 .LBB0_1352
